# A/B: per-phase s_setprio 1/0 flips removed from the three main GEMM K-loops (priority left at 0 throughout)
# speedup vs baseline: 1.0052x; 1.0046x over previous
; #define G_STAGE(bufoff, gbase, v0, v1) do { \
;     __builtin_amdgcn_global_load_lds((const unsigned*)((const char*)(gbase) + (v0)), (LAS unsigned*)(lds + (bufoff) + ldsw), 16, 0, 0); \
;     __builtin_amdgcn_global_load_lds((const unsigned*)((const char*)(gbase) + (v1)), (LAS unsigned*)(lds + (bufoff) + ldsw + 8192), 16, 0, 0); } while (0)
; #define G_LDA(dst, b, h) do { _Pragma("unroll") for (int m = 0; m < 4; ++m) _Pragma("unroll") for (int k = 0; k < 2; ++k) dst[m][k] = *(const LAS bf16x8*)(lds + G_SA(b, h) + aoff + m * 2048 + k * 1024); } while (0)
; #define G_LDB(dst, b, h) do { _Pragma("unroll") for (int n = 0; n < 2; ++n) _Pragma("unroll") for (int k = 0; k < 2; ++k) dst[n][k] = *(const LAS bf16x8*)(lds + G_SB(b, h) + boff + n * 2048 + k * 1024); } while (0)
; #define G_MMA(ai, bj, At, Bt) do { __builtin_amdgcn_s_setprio(1); _Pragma("unroll") for (int m = 0; m < 4; ++m) _Pragma("unroll") for (int n = 0; n < 2; ++n) _Pragma("unroll") for (int k = 0; k < 2; ++k) \
;     acc[ai][bj][m][n] = __builtin_amdgcn_mfma_f32_16x16x32_bf16(Bt[n][k], At[m][k], acc[ai][bj][m][n], 0, 0, 0); __builtin_amdgcn_s_setprio(0); } while (0)
; #define G_WAIT_V(n) asm volatile("s_waitcnt vmcnt(" #n ")" ::: "memory")
; #define G_WAIT_L(n) asm volatile("s_waitcnt lgkmcnt(" #n ")" ::: "memory")
; #define G_BAR __builtin_amdgcn_s_barrier()
; __device__ __forceinline__ void gemm_run(const Params& p, int l, int kind, int single) {
;     ...
;     for (int t = 0; t < nt; t += 2) {
;       const bool last = (t == nt - 2);
;       const char* a1 = cA + (size_t)(t + 1) * kstep;
;       const char* a2 = last ? nA : cA + (size_t)(t + 2) * kstep; const char* b2 = last ? nB : cB + (size_t)(t + 2) * kstep;
;       const char* a3 = a2 + kstep; const char* b3 = b2 + kstep;
;       const unsigned w0 = last ? vn0 : vc0, w1 = last ? vn1 : vc1; const size_t h2 = last ? hn : hc;
;       G_LDB(B0, 0, 0); G_SCHED; G_LDA(At, 0, 0); G_STAGE(G_SA(1, 1), a1 + hc, vc0, vc1);
;       G_WAIT_L(8); G_BAR; G_WAIT_L(0); G_MMA(0, 0, At, B0); G_BAR; G_SCHED;
;       G_LDB(B1, 0, 1); G_STAGE(G_SB(0, 0), b2, w0, w1);
;       G_BAR; G_WAIT_L(0); G_MMA(0, 1, At, B1); G_BAR;
;       G_LDA(At, 0, 1); G_STAGE(G_SA(0, 0), a2, w0, w1);
;       G_BAR; G_WAIT_L(0); G_MMA(1, 0, At, B0); G_BAR; G_SCHED;
;       G_STAGE(G_SB(0, 1), b2 + h2, w0, w1);
;       G_WAIT_V(6); G_BAR; G_MMA(1, 1, At, B1); G_BAR;
.LBB0_94:
	s_add_u32 s8, s0, 0xfffc0080
	s_addc_u32 s9, s1, -1
	s_cmp_eq_u32 s24, 12
	s_cselect_b32 s21, s13, s9
	s_cselect_b32 s20, s12, s8
	s_cselect_b32 s9, s15, s11
	s_cselect_b32 s8, s14, s5
	s_add_i32 s25, s89, 0x100
	v_add_u32_e32 v140, s25, v172
	ds_read_b128 v[128:131], v140
	ds_read_b128 v[132:135], v140 offset:1024
	ds_read_b128 v[136:139], v140 offset:2048
	ds_read_b128 v[140:143], v140 offset:3072
	v_lshl_add_u64 v[186:187], s[0:1], 0, v[156:157]
	s_add_i32 m0, s27, 0xc000
	ds_read_b128 v[144:147], v173
	ds_read_b128 v[148:151], v173 offset:1024
	ds_read_b128 v[160:163], v173 offset:2048
	ds_read_b128 v[164:167], v173 offset:3072
	ds_read_b128 v[168:171], v173 offset:4096
	ds_read_b128 v[174:177], v173 offset:5120
	ds_read_b128 v[178:181], v173 offset:6144
	ds_read_b128 v[182:185], v173 offset:7168
	global_load_lds_dwordx4 v[186:187], off
	v_lshl_add_u64 v[186:187], s[0:1], 0, v[158:159]
	s_add_i32 m0, s27, 0xe000
	s_nop 0
	global_load_lds_dwordx4 v[186:187], off
	s_waitcnt lgkmcnt(8)
	s_barrier
	s_waitcnt lgkmcnt(0)
	v_mfma_f32_16x16x32_bf16 v[124:127], v[128:131], v[144:147], v[124:127]
	v_mfma_f32_16x16x32_bf16 v[120:123], v[136:139], v[144:147], v[120:123]
	v_mfma_f32_16x16x32_bf16 v[108:111], v[128:131], v[160:163], v[108:111]
	v_mfma_f32_16x16x32_bf16 v[104:107], v[136:139], v[160:163], v[104:107]
	v_mfma_f32_16x16x32_bf16 v[92:95], v[128:131], v[168:171], v[92:95]
	v_mfma_f32_16x16x32_bf16 v[88:91], v[136:139], v[168:171], v[88:91]
	v_mfma_f32_16x16x32_bf16 v[76:79], v[128:131], v[178:181], v[76:79]
	v_mfma_f32_16x16x32_bf16 v[72:75], v[136:139], v[178:181], v[72:75]
	v_mfma_f32_16x16x32_bf16 v[124:127], v[132:135], v[148:151], v[124:127]
	v_mfma_f32_16x16x32_bf16 v[120:123], v[140:143], v[148:151], v[120:123]
	v_mfma_f32_16x16x32_bf16 v[108:111], v[132:135], v[164:167], v[108:111]
	v_mfma_f32_16x16x32_bf16 v[104:107], v[140:143], v[164:167], v[104:107]
	v_mfma_f32_16x16x32_bf16 v[92:95], v[132:135], v[174:177], v[92:95]
	v_mfma_f32_16x16x32_bf16 v[88:91], v[140:143], v[174:177], v[88:91]
	v_mfma_f32_16x16x32_bf16 v[76:79], v[132:135], v[182:185], v[76:79]
	v_mfma_f32_16x16x32_bf16 v[72:75], v[140:143], v[182:185], v[72:75]
	s_barrier
	s_add_i32 s47, s90, 0x100
	v_add_u32_e32 v186, s47, v172
	s_add_i32 s25, s25, s3
	ds_read_b128 v[200:203], v186
	ds_read_b128 v[204:207], v186 offset:1024
	ds_read_b128 v[218:221], v186 offset:2048
	ds_read_b128 v[222:225], v186 offset:3072
	v_lshl_add_u64 v[186:187], s[8:9], 0, v[152:153]
	s_mov_b32 m0, s25
	v_lshl_add_u64 v[226:227], s[8:9], 0, v[154:155]
	global_load_lds_dwordx4 v[186:187], off
	s_add_i32 m0, s25, 0x2000
	s_nop 0
	global_load_lds_dwordx4 v[226:227], off
	s_barrier
	s_waitcnt lgkmcnt(0)
	v_mfma_f32_16x16x32_bf16 v[116:119], v[200:203], v[144:147], v[116:119]
	v_mfma_f32_16x16x32_bf16 v[112:115], v[218:221], v[144:147], v[112:115]
	v_mfma_f32_16x16x32_bf16 v[100:103], v[200:203], v[160:163], v[100:103]
	v_mfma_f32_16x16x32_bf16 v[96:99], v[218:221], v[160:163], v[96:99]
	v_mfma_f32_16x16x32_bf16 v[84:87], v[200:203], v[168:171], v[84:87]
	v_mfma_f32_16x16x32_bf16 v[80:83], v[218:221], v[168:171], v[80:83]
	v_mfma_f32_16x16x32_bf16 v[68:71], v[200:203], v[178:181], v[68:71]
	v_mfma_f32_16x16x32_bf16 v[64:67], v[218:221], v[178:181], v[64:67]
	v_mfma_f32_16x16x32_bf16 v[116:119], v[204:207], v[148:151], v[116:119]
	v_mfma_f32_16x16x32_bf16 v[112:115], v[222:225], v[148:151], v[112:115]
	v_mfma_f32_16x16x32_bf16 v[100:103], v[204:207], v[164:167], v[100:103]
	v_mfma_f32_16x16x32_bf16 v[96:99], v[222:225], v[164:167], v[96:99]
	v_mfma_f32_16x16x32_bf16 v[84:87], v[204:207], v[174:177], v[84:87]
	v_mfma_f32_16x16x32_bf16 v[80:83], v[222:225], v[174:177], v[80:83]
	v_mfma_f32_16x16x32_bf16 v[68:71], v[204:207], v[182:185], v[68:71]
	v_mfma_f32_16x16x32_bf16 v[64:67], v[222:225], v[182:185], v[64:67]
	s_mov_b32 m0, s27
	v_lshl_add_u64 v[228:229], s[20:21], 0, v[152:153]
	s_barrier
	ds_read_b128 v[144:147], v173 offset:16384
	ds_read_b128 v[148:151], v173 offset:17408
	ds_read_b128 v[160:163], v173 offset:18432
	ds_read_b128 v[164:167], v173 offset:19456
	ds_read_b128 v[168:171], v173 offset:20480
	ds_read_b128 v[174:177], v173 offset:21504
	ds_read_b128 v[178:181], v173 offset:22528
	ds_read_b128 v[182:185], v173 offset:23552
	global_load_lds_dwordx4 v[228:229], off
	v_lshl_add_u64 v[230:231], s[20:21], 0, v[154:155]
	s_mov_b32 m0, s28
	s_nop 0
	global_load_lds_dwordx4 v[230:231], off
	s_barrier
	s_waitcnt lgkmcnt(0)
	v_mfma_f32_16x16x32_bf16 v[60:63], v[128:131], v[144:147], v[60:63]
	v_mfma_f32_16x16x32_bf16 v[56:59], v[136:139], v[144:147], v[56:59]
	v_mfma_f32_16x16x32_bf16 v[44:47], v[128:131], v[160:163], v[44:47]
	v_mfma_f32_16x16x32_bf16 v[40:43], v[136:139], v[160:163], v[40:43]
	v_mfma_f32_16x16x32_bf16 v[28:31], v[128:131], v[168:171], v[28:31]
	v_mfma_f32_16x16x32_bf16 v[24:27], v[136:139], v[168:171], v[24:27]
	v_mfma_f32_16x16x32_bf16 v[12:15], v[128:131], v[178:181], v[12:15]
	v_mfma_f32_16x16x32_bf16 v[8:11], v[136:139], v[178:181], v[8:11]
	v_mfma_f32_16x16x32_bf16 v[60:63], v[132:135], v[148:151], v[60:63]
	v_mfma_f32_16x16x32_bf16 v[56:59], v[140:143], v[148:151], v[56:59]
	v_mfma_f32_16x16x32_bf16 v[44:47], v[132:135], v[164:167], v[44:47]
	v_mfma_f32_16x16x32_bf16 v[40:43], v[140:143], v[164:167], v[40:43]
	v_mfma_f32_16x16x32_bf16 v[28:31], v[132:135], v[174:177], v[28:31]
	v_mfma_f32_16x16x32_bf16 v[24:27], v[140:143], v[174:177], v[24:27]
	v_mfma_f32_16x16x32_bf16 v[12:15], v[132:135], v[182:185], v[12:15]
	v_mfma_f32_16x16x32_bf16 v[8:11], v[140:143], v[182:185], v[8:11]
	s_barrier
; #define G_STAGE(bufoff, gbase, v0, v1) do { \
;     __builtin_amdgcn_global_load_lds((const unsigned*)((const char*)(gbase) + (v0)), (LAS unsigned*)(lds + (bufoff) + ldsw), 16, 0, 0); \
;     __builtin_amdgcn_global_load_lds((const unsigned*)((const char*)(gbase) + (v1)), (LAS unsigned*)(lds + (bufoff) + ldsw + 8192), 16, 0, 0); } while (0)
; #define G_LDA(dst, b, h) do { _Pragma("unroll") for (int m = 0; m < 4; ++m) _Pragma("unroll") for (int k = 0; k < 2; ++k) dst[m][k] = *(const LAS bf16x8*)(lds + G_SA(b, h) + aoff + m * 2048 + k * 1024); } while (0)
; #define G_LDB(dst, b, h) do { _Pragma("unroll") for (int n = 0; n < 2; ++n) _Pragma("unroll") for (int k = 0; k < 2; ++k) dst[n][k] = *(const LAS bf16x8*)(lds + G_SB(b, h) + boff + n * 2048 + k * 1024); } while (0)
; #define G_MMA(ai, bj, At, Bt) do { __builtin_amdgcn_s_setprio(1); _Pragma("unroll") for (int m = 0; m < 4; ++m) _Pragma("unroll") for (int n = 0; n < 2; ++n) _Pragma("unroll") for (int k = 0; k < 2; ++k) \
;     acc[ai][bj][m][n] = __builtin_amdgcn_mfma_f32_16x16x32_bf16(Bt[n][k], At[m][k], acc[ai][bj][m][n], 0, 0, 0); __builtin_amdgcn_s_setprio(0); } while (0)
; #define G_WAIT_V(n) asm volatile("s_waitcnt vmcnt(" #n ")" ::: "memory")
; #define G_WAIT_L(n) asm volatile("s_waitcnt lgkmcnt(" #n ")" ::: "memory")
; #define G_BAR __builtin_amdgcn_s_barrier()
; #define G_SCHED __builtin_amdgcn_sched_barrier(0)
; __device__ __forceinline__ void gemm_run(const Params& p, int l, int kind, int single) {
;     ...
;       G_STAGE(G_SB(0, 1), b2 + h2, w0, w1);
;       G_WAIT_V(6); G_BAR; G_MMA(1, 1, At, B1); G_BAR;
;       G_LDB(B0, 1, 0); G_SCHED; G_LDA(At, 1, 0); G_STAGE(G_SA(0, 1), a2 + h2, w0, w1);
;       G_WAIT_L(8); G_BAR; G_WAIT_L(0); G_MMA(0, 0, At, B0); G_BAR; G_SCHED;
;       G_LDB(B1, 1, 1); G_STAGE(G_SB(1, 0), b3, w0, w1);
;       G_BAR; G_WAIT_L(0); G_MMA(0, 1, At, B1); G_BAR;
;       G_LDA(At, 1, 1); G_STAGE(G_SA(1, 0), a3, w0, w1);
	s_add_u32 s48, s8, 0x40000
	s_addc_u32 s49, s9, 0
	s_add_i32 s25, s47, s3
	v_lshl_add_u64 v[128:129], s[48:49], 0, v[152:153]
	s_mov_b32 m0, s25
	s_nop 0
	global_load_lds_dwordx4 v[128:129], off
	v_lshl_add_u64 v[128:129], s[48:49], 0, v[154:155]
	s_add_i32 m0, s25, 0x2000
	s_nop 0
	global_load_lds_dwordx4 v[128:129], off
	s_waitcnt vmcnt(6)
	s_barrier
	v_mfma_f32_16x16x32_bf16 v[52:55], v[200:203], v[144:147], v[52:55]
	v_mfma_f32_16x16x32_bf16 v[48:51], v[218:221], v[144:147], v[48:51]
	v_mfma_f32_16x16x32_bf16 v[36:39], v[200:203], v[160:163], v[36:39]
	v_mfma_f32_16x16x32_bf16 v[32:35], v[218:221], v[160:163], v[32:35]
	v_mfma_f32_16x16x32_bf16 v[20:23], v[200:203], v[168:171], v[20:23]
	v_mfma_f32_16x16x32_bf16 v[16:19], v[218:221], v[168:171], v[16:19]
	v_mfma_f32_16x16x32_bf16 v[4:7], v[200:203], v[178:181], v[4:7]
	v_mfma_f32_16x16x32_bf16 v[0:3], v[218:221], v[178:181], v[0:3]
	v_mfma_f32_16x16x32_bf16 v[52:55], v[204:207], v[148:151], v[52:55]
	v_mfma_f32_16x16x32_bf16 v[48:51], v[222:225], v[148:151], v[48:51]
	v_mfma_f32_16x16x32_bf16 v[36:39], v[204:207], v[164:167], v[36:39]
	v_mfma_f32_16x16x32_bf16 v[32:35], v[222:225], v[164:167], v[32:35]
	v_mfma_f32_16x16x32_bf16 v[20:23], v[204:207], v[174:177], v[20:23]
	v_mfma_f32_16x16x32_bf16 v[16:19], v[222:225], v[174:177], v[16:19]
	v_mfma_f32_16x16x32_bf16 v[4:7], v[204:207], v[182:185], v[4:7]
	v_mfma_f32_16x16x32_bf16 v[0:3], v[222:225], v[182:185], v[0:3]
	s_add_i32 s25, s91, 0x100
	v_add_u32_e32 v140, s25, v172
	s_barrier
	ds_read_b128 v[128:131], v140
	ds_read_b128 v[132:135], v140 offset:1024
	ds_read_b128 v[136:139], v140 offset:2048
	ds_read_b128 v[140:143], v140 offset:3072
	s_add_u32 s20, s20, 0x40000
	s_addc_u32 s21, s21, 0
	s_mov_b32 m0, s29
	v_lshl_add_u64 v[200:201], s[20:21], 0, v[152:153]
	ds_read_b128 v[144:147], v173 offset:32768
	ds_read_b128 v[148:151], v173 offset:33792
	ds_read_b128 v[160:163], v173 offset:34816
	ds_read_b128 v[164:167], v173 offset:35840
	ds_read_b128 v[168:171], v173 offset:36864
	ds_read_b128 v[174:177], v173 offset:37888
	ds_read_b128 v[178:181], v173 offset:38912
	ds_read_b128 v[182:185], v173 offset:39936
	global_load_lds_dwordx4 v[200:201], off
	v_lshl_add_u64 v[200:201], s[20:21], 0, v[154:155]
	s_mov_b32 m0, s30
	s_nop 0
	global_load_lds_dwordx4 v[200:201], off
	s_waitcnt lgkmcnt(8)
	s_barrier
	s_waitcnt lgkmcnt(0)
	v_mfma_f32_16x16x32_bf16 v[124:127], v[128:131], v[144:147], v[124:127]
	v_mfma_f32_16x16x32_bf16 v[120:123], v[136:139], v[144:147], v[120:123]
	v_mfma_f32_16x16x32_bf16 v[108:111], v[128:131], v[160:163], v[108:111]
	v_mfma_f32_16x16x32_bf16 v[104:107], v[136:139], v[160:163], v[104:107]
	v_mfma_f32_16x16x32_bf16 v[92:95], v[128:131], v[168:171], v[92:95]
	v_mfma_f32_16x16x32_bf16 v[88:91], v[136:139], v[168:171], v[88:91]
	v_mfma_f32_16x16x32_bf16 v[76:79], v[128:131], v[178:181], v[76:79]
	v_mfma_f32_16x16x32_bf16 v[72:75], v[136:139], v[178:181], v[72:75]
	v_mfma_f32_16x16x32_bf16 v[124:127], v[132:135], v[148:151], v[124:127]
	v_mfma_f32_16x16x32_bf16 v[120:123], v[140:143], v[148:151], v[120:123]
	v_mfma_f32_16x16x32_bf16 v[108:111], v[132:135], v[164:167], v[108:111]
	v_mfma_f32_16x16x32_bf16 v[104:107], v[140:143], v[164:167], v[104:107]
	v_mfma_f32_16x16x32_bf16 v[92:95], v[132:135], v[174:177], v[92:95]
	v_mfma_f32_16x16x32_bf16 v[88:91], v[140:143], v[174:177], v[88:91]
	v_mfma_f32_16x16x32_bf16 v[76:79], v[132:135], v[182:185], v[76:79]
	v_mfma_f32_16x16x32_bf16 v[72:75], v[140:143], v[182:185], v[72:75]
	s_barrier
	s_add_i32 s20, s94, 0x100
	s_add_i32 s21, s25, s3
	v_add_u32_e32 v190, s20, v172
	v_lshl_add_u64 v[186:187], v[186:187], 0, s[96:97]
	s_mov_b32 m0, s21
	ds_read_b128 v[200:203], v190
	ds_read_b128 v[204:207], v190 offset:1024
	ds_read_b128 v[218:221], v190 offset:2048
	ds_read_b128 v[222:225], v190 offset:3072
	global_load_lds_dwordx4 v[186:187], off
	v_lshl_add_u64 v[186:187], v[226:227], 0, s[96:97]
	s_add_i32 m0, s21, 0x2000
	s_nop 0
	global_load_lds_dwordx4 v[186:187], off
	s_barrier
; #define G_STAGE(bufoff, gbase, v0, v1) do { \
;     __builtin_amdgcn_global_load_lds((const unsigned*)((const char*)(gbase) + (v0)), (LAS unsigned*)(lds + (bufoff) + ldsw), 16, 0, 0); \
;     __builtin_amdgcn_global_load_lds((const unsigned*)((const char*)(gbase) + (v1)), (LAS unsigned*)(lds + (bufoff) + ldsw + 8192), 16, 0, 0); } while (0)
; #define G_MMA(ai, bj, At, Bt) do { __builtin_amdgcn_s_setprio(1); _Pragma("unroll") for (int m = 0; m < 4; ++m) _Pragma("unroll") for (int n = 0; n < 2; ++n) _Pragma("unroll") for (int k = 0; k < 2; ++k) \
;     acc[ai][bj][m][n] = __builtin_amdgcn_mfma_f32_16x16x32_bf16(Bt[n][k], At[m][k], acc[ai][bj][m][n], 0, 0, 0); __builtin_amdgcn_s_setprio(0); } while (0)
; #define G_WAIT_V(n) asm volatile("s_waitcnt vmcnt(" #n ")" ::: "memory")
; #define G_WAIT_L(n) asm volatile("s_waitcnt lgkmcnt(" #n ")" ::: "memory")
; #define G_BAR __builtin_amdgcn_s_barrier()
; #define G_SCHED __builtin_amdgcn_sched_barrier(0)
; __device__ __forceinline__ void gemm_run(const Params& p, int l, int kind, int single) {
;     ...
;     for (int t = 0; t < nt; t += 2) {
;       const bool last = (t == nt - 2);
;       const char* a1 = cA + (size_t)(t + 1) * kstep;
;       const char* a2 = last ? nA : cA + (size_t)(t + 2) * kstep; const char* b2 = last ? nB : cB + (size_t)(t + 2) * kstep;
;     ...
;       G_BAR; G_WAIT_L(0); G_MMA(1, 0, At, B0); G_BAR; G_SCHED;
;       G_STAGE(G_SB(1, 1), b3 + h2, w0, w1);
;       G_WAIT_V(6); G_BAR; G_MMA(1, 1, At, B1); G_BAR;
	s_waitcnt lgkmcnt(0)
	v_mfma_f32_16x16x32_bf16 v[116:119], v[200:203], v[144:147], v[116:119]
	v_mfma_f32_16x16x32_bf16 v[112:115], v[218:221], v[144:147], v[112:115]
	v_mfma_f32_16x16x32_bf16 v[100:103], v[200:203], v[160:163], v[100:103]
	v_mfma_f32_16x16x32_bf16 v[96:99], v[218:221], v[160:163], v[96:99]
	v_mfma_f32_16x16x32_bf16 v[84:87], v[200:203], v[168:171], v[84:87]
	v_mfma_f32_16x16x32_bf16 v[80:83], v[218:221], v[168:171], v[80:83]
	v_mfma_f32_16x16x32_bf16 v[68:71], v[200:203], v[178:181], v[68:71]
	v_mfma_f32_16x16x32_bf16 v[64:67], v[218:221], v[178:181], v[64:67]
	v_mfma_f32_16x16x32_bf16 v[116:119], v[204:207], v[148:151], v[116:119]
	v_mfma_f32_16x16x32_bf16 v[112:115], v[222:225], v[148:151], v[112:115]
	v_mfma_f32_16x16x32_bf16 v[100:103], v[204:207], v[164:167], v[100:103]
	v_mfma_f32_16x16x32_bf16 v[96:99], v[222:225], v[164:167], v[96:99]
	v_mfma_f32_16x16x32_bf16 v[84:87], v[204:207], v[174:177], v[84:87]
	v_mfma_f32_16x16x32_bf16 v[80:83], v[222:225], v[174:177], v[80:83]
	v_mfma_f32_16x16x32_bf16 v[68:71], v[204:207], v[182:185], v[68:71]
	v_mfma_f32_16x16x32_bf16 v[64:67], v[222:225], v[182:185], v[64:67]
	s_mov_b32 m0, s31
	v_lshl_add_u64 v[186:187], v[228:229], 0, s[96:97]
	s_barrier
	ds_read_b128 v[144:147], v173 offset:49152
	ds_read_b128 v[148:151], v173 offset:50176
	ds_read_b128 v[160:163], v173 offset:51200
	ds_read_b128 v[164:167], v173 offset:52224
	ds_read_b128 v[168:171], v173 offset:53248
	ds_read_b128 v[174:177], v173 offset:54272
	ds_read_b128 v[178:181], v173 offset:55296
	ds_read_b128 v[182:185], v173 offset:56320
	global_load_lds_dwordx4 v[186:187], off
	v_lshl_add_u64 v[186:187], v[230:231], 0, s[96:97]
	s_mov_b32 m0, s34
	s_nop 0
	global_load_lds_dwordx4 v[186:187], off
	s_barrier
	s_waitcnt lgkmcnt(0)
	v_mfma_f32_16x16x32_bf16 v[60:63], v[128:131], v[144:147], v[60:63]
	v_mfma_f32_16x16x32_bf16 v[56:59], v[136:139], v[144:147], v[56:59]
	v_mfma_f32_16x16x32_bf16 v[44:47], v[128:131], v[160:163], v[44:47]
	v_mfma_f32_16x16x32_bf16 v[40:43], v[136:139], v[160:163], v[40:43]
	v_mfma_f32_16x16x32_bf16 v[28:31], v[128:131], v[168:171], v[28:31]
	v_mfma_f32_16x16x32_bf16 v[24:27], v[136:139], v[168:171], v[24:27]
	v_mfma_f32_16x16x32_bf16 v[12:15], v[128:131], v[178:181], v[12:15]
	v_mfma_f32_16x16x32_bf16 v[8:11], v[136:139], v[178:181], v[8:11]
	v_mfma_f32_16x16x32_bf16 v[60:63], v[132:135], v[148:151], v[60:63]
	v_mfma_f32_16x16x32_bf16 v[56:59], v[140:143], v[148:151], v[56:59]
	v_mfma_f32_16x16x32_bf16 v[44:47], v[132:135], v[164:167], v[44:47]
	v_mfma_f32_16x16x32_bf16 v[40:43], v[140:143], v[164:167], v[40:43]
	v_mfma_f32_16x16x32_bf16 v[28:31], v[132:135], v[174:177], v[28:31]
	v_mfma_f32_16x16x32_bf16 v[24:27], v[140:143], v[174:177], v[24:27]
	v_mfma_f32_16x16x32_bf16 v[12:15], v[132:135], v[182:185], v[12:15]
	v_mfma_f32_16x16x32_bf16 v[8:11], v[140:143], v[182:185], v[8:11]
	s_barrier
	s_add_u32 s8, s8, 0x40080
	s_addc_u32 s9, s9, 0
	s_add_i32 s20, s20, s3
	v_lshl_add_u64 v[128:129], s[8:9], 0, v[152:153]
	s_mov_b32 m0, s20
	s_nop 0
	global_load_lds_dwordx4 v[128:129], off
	v_lshl_add_u64 v[128:129], s[8:9], 0, v[154:155]
	s_add_i32 m0, s20, 0x2000
	s_nop 0
	global_load_lds_dwordx4 v[128:129], off
	s_waitcnt vmcnt(6)
	s_barrier
	v_mfma_f32_16x16x32_bf16 v[52:55], v[200:203], v[144:147], v[52:55]
	v_mfma_f32_16x16x32_bf16 v[48:51], v[218:221], v[144:147], v[48:51]
	v_mfma_f32_16x16x32_bf16 v[36:39], v[200:203], v[160:163], v[36:39]
	v_mfma_f32_16x16x32_bf16 v[32:35], v[218:221], v[160:163], v[32:35]
	v_mfma_f32_16x16x32_bf16 v[20:23], v[200:203], v[168:171], v[20:23]
	v_mfma_f32_16x16x32_bf16 v[16:19], v[218:221], v[168:171], v[16:19]
	v_mfma_f32_16x16x32_bf16 v[4:7], v[200:203], v[178:181], v[4:7]
	v_mfma_f32_16x16x32_bf16 v[0:3], v[218:221], v[178:181], v[0:3]
	v_mfma_f32_16x16x32_bf16 v[52:55], v[204:207], v[148:151], v[52:55]
	v_mfma_f32_16x16x32_bf16 v[48:51], v[222:225], v[148:151], v[48:51]
	v_mfma_f32_16x16x32_bf16 v[36:39], v[204:207], v[164:167], v[36:39]
	v_mfma_f32_16x16x32_bf16 v[32:35], v[222:225], v[164:167], v[32:35]
	v_mfma_f32_16x16x32_bf16 v[20:23], v[204:207], v[174:177], v[20:23]
	v_mfma_f32_16x16x32_bf16 v[16:19], v[222:225], v[174:177], v[16:19]
	v_mfma_f32_16x16x32_bf16 v[4:7], v[204:207], v[182:185], v[4:7]
	v_mfma_f32_16x16x32_bf16 v[0:3], v[222:225], v[182:185], v[0:3]
	s_add_i32 s24, s24, 2
	s_add_u32 s0, s0, 0x100
	s_addc_u32 s1, s1, 0
	s_add_u32 s5, s5, 0x100
	s_addc_u32 s11, s11, 0
	s_cmp_gt_u32 s24, 13
	s_barrier
	s_cbranch_scc0 .LBB0_94
	s_cmpk_gt_u32 s2, 0xff
	s_cbranch_scc1 .Lal1_a
	s_barrier

; #define G_STAGE(bufoff, gbase, v0, v1) do { \
;     __builtin_amdgcn_global_load_lds((const unsigned*)((const char*)(gbase) + (v0)), (LAS unsigned*)(lds + (bufoff) + ldsw), 16, 0, 0); \
;     __builtin_amdgcn_global_load_lds((const unsigned*)((const char*)(gbase) + (v1)), (LAS unsigned*)(lds + (bufoff) + ldsw + 8192), 16, 0, 0); } while (0)
; #define G_LDA(dst, b, h) do { _Pragma("unroll") for (int m = 0; m < 4; ++m) _Pragma("unroll") for (int k = 0; k < 2; ++k) dst[m][k] = *(const LAS bf16x8*)(lds + G_SA(b, h) + aoff + m * 2048 + k * 1024); } while (0)
; #define G_LDB(dst, b, h) do { _Pragma("unroll") for (int n = 0; n < 2; ++n) _Pragma("unroll") for (int k = 0; k < 2; ++k) dst[n][k] = *(const LAS bf16x8*)(lds + G_SB(b, h) + boff + n * 2048 + k * 1024); } while (0)
; #define G_MMA(ai, bj, At, Bt) do { __builtin_amdgcn_s_setprio(1); _Pragma("unroll") for (int m = 0; m < 4; ++m) _Pragma("unroll") for (int n = 0; n < 2; ++n) _Pragma("unroll") for (int k = 0; k < 2; ++k) \
;     acc[ai][bj][m][n] = __builtin_amdgcn_mfma_f32_16x16x32_bf16(Bt[n][k], At[m][k], acc[ai][bj][m][n], 0, 0, 0); __builtin_amdgcn_s_setprio(0); } while (0)
; #define G_WAIT_L(n) asm volatile("s_waitcnt lgkmcnt(" #n ")" ::: "memory")
; #define G_BAR __builtin_amdgcn_s_barrier()
; #define G_SCHED __builtin_amdgcn_sched_barrier(0)
; __device__ __forceinline__ void gemm_run(const Params& p, int l, int kind, int single) {
;     ...
;       G_LDB(B0, 0, 0); G_SCHED; G_LDA(At, 0, 0); G_STAGE(G_SA(1, 1), a1 + hc, vc0, vc1);
;       G_WAIT_L(8); G_BAR; G_WAIT_L(0); G_MMA(0, 0, At, B0); G_BAR; G_SCHED;
;       G_LDB(B1, 0, 1); G_STAGE(G_SB(0, 0), b2, w0, w1);
;       G_BAR; G_WAIT_L(0); G_MMA(0, 1, At, B1); G_BAR;
;       G_LDA(At, 0, 1); G_STAGE(G_SA(0, 0), a2, w0, w1);
;       G_BAR; G_WAIT_L(0); G_MMA(1, 0, At, B0); G_BAR; G_SCHED;
.LBB0_907:
	s_add_i32 s15, s15, 2
	s_add_u32 s44, s12, 0x80
	s_addc_u32 s45, s13, 0
	s_and_b64 s[28:29], exec, s[28:29]
	s_cselect_b32 s29, s5, s45
	s_cselect_b32 s28, s4, s44
	s_add_i32 s44, s89, 0x100
	v_add_u32_e32 v150, s44, v221
	ds_read_b128 v[138:141], v150
	ds_read_b128 v[142:145], v150 offset:1024
	ds_read_b128 v[146:149], v150 offset:2048
	ds_read_b128 v[150:153], v150 offset:3072
	v_lshl_add_u64 v[186:187], s[12:13], 0, v[130:131]
	s_add_i32 m0, s34, 0xc000
	ds_read_b128 v[154:157], v222
	ds_read_b128 v[158:161], v222 offset:1024
	ds_read_b128 v[162:165], v222 offset:2048
	ds_read_b128 v[166:169], v222 offset:3072
	ds_read_b128 v[170:173], v222 offset:4096
	ds_read_b128 v[174:177], v222 offset:5120
	ds_read_b128 v[178:181], v222 offset:6144
	ds_read_b128 v[182:185], v222 offset:7168
	global_load_lds_dwordx4 v[186:187], off
	v_lshl_add_u64 v[186:187], s[12:13], 0, v[132:133]
	s_add_i32 m0, s34, 0xe000
	s_nop 0
	global_load_lds_dwordx4 v[186:187], off
	s_waitcnt lgkmcnt(8)
	s_barrier
	s_waitcnt lgkmcnt(0)
	v_mfma_f32_16x16x32_bf16 v[124:127], v[138:141], v[154:157], v[124:127]
	v_mfma_f32_16x16x32_bf16 v[120:123], v[146:149], v[154:157], v[120:123]
	v_mfma_f32_16x16x32_bf16 v[116:119], v[138:141], v[162:165], v[116:119]
	v_mfma_f32_16x16x32_bf16 v[112:115], v[146:149], v[162:165], v[112:115]
	v_mfma_f32_16x16x32_bf16 v[108:111], v[138:141], v[170:173], v[108:111]
	v_mfma_f32_16x16x32_bf16 v[104:107], v[146:149], v[170:173], v[104:107]
	v_mfma_f32_16x16x32_bf16 v[100:103], v[138:141], v[178:181], v[100:103]
	v_mfma_f32_16x16x32_bf16 v[96:99], v[146:149], v[178:181], v[96:99]
	v_mfma_f32_16x16x32_bf16 v[124:127], v[142:145], v[158:161], v[124:127]
	v_mfma_f32_16x16x32_bf16 v[120:123], v[150:153], v[158:161], v[120:123]
	v_mfma_f32_16x16x32_bf16 v[116:119], v[142:145], v[166:169], v[116:119]
	v_mfma_f32_16x16x32_bf16 v[112:115], v[150:153], v[166:169], v[112:115]
	v_mfma_f32_16x16x32_bf16 v[108:111], v[142:145], v[174:177], v[108:111]
	v_mfma_f32_16x16x32_bf16 v[104:107], v[150:153], v[174:177], v[104:107]
	v_mfma_f32_16x16x32_bf16 v[100:103], v[142:145], v[182:185], v[100:103]
	v_mfma_f32_16x16x32_bf16 v[96:99], v[150:153], v[182:185], v[96:99]
	s_barrier
	s_add_i32 s45, s90, 0x100
	v_add_u32_e32 v186, s45, v221
	s_add_i32 s44, s44, s31
	ds_read_b128 v[204:207], v186
	ds_read_b128 v[224:227], v186 offset:1024
	ds_read_b128 v[228:231], v186 offset:2048
	ds_read_b128 v[232:235], v186 offset:3072
	v_lshl_add_u64 v[186:187], s[26:27], 0, v[136:137]
	s_mov_b32 m0, s44
	v_lshl_add_u64 v[236:237], s[26:27], 0, v[134:135]
	global_load_lds_dwordx4 v[186:187], off
	s_add_i32 m0, s44, 0x2000
	s_nop 0
	global_load_lds_dwordx4 v[236:237], off
	s_barrier
	s_waitcnt lgkmcnt(0)
	v_mfma_f32_16x16x32_bf16 v[92:95], v[204:207], v[154:157], v[92:95]
	v_mfma_f32_16x16x32_bf16 v[88:91], v[228:231], v[154:157], v[88:91]
	v_mfma_f32_16x16x32_bf16 v[84:87], v[204:207], v[162:165], v[84:87]
	v_mfma_f32_16x16x32_bf16 v[80:83], v[228:231], v[162:165], v[80:83]
	v_mfma_f32_16x16x32_bf16 v[76:79], v[204:207], v[170:173], v[76:79]
	v_mfma_f32_16x16x32_bf16 v[72:75], v[228:231], v[170:173], v[72:75]
	v_mfma_f32_16x16x32_bf16 v[68:71], v[204:207], v[178:181], v[68:71]
	v_mfma_f32_16x16x32_bf16 v[64:67], v[228:231], v[178:181], v[64:67]
	v_mfma_f32_16x16x32_bf16 v[92:95], v[224:227], v[158:161], v[92:95]
	v_mfma_f32_16x16x32_bf16 v[88:91], v[232:235], v[158:161], v[88:91]
	v_mfma_f32_16x16x32_bf16 v[84:87], v[224:227], v[166:169], v[84:87]
	v_mfma_f32_16x16x32_bf16 v[80:83], v[232:235], v[166:169], v[80:83]
	v_mfma_f32_16x16x32_bf16 v[76:79], v[224:227], v[174:177], v[76:79]
	v_mfma_f32_16x16x32_bf16 v[72:75], v[232:235], v[174:177], v[72:75]
	v_mfma_f32_16x16x32_bf16 v[68:71], v[224:227], v[182:185], v[68:71]
	v_mfma_f32_16x16x32_bf16 v[64:67], v[232:235], v[182:185], v[64:67]
	s_mov_b32 m0, s34
	v_lshl_add_u64 v[238:239], s[28:29], 0, v[136:137]
	s_barrier
	ds_read_b128 v[154:157], v222 offset:16384
	ds_read_b128 v[158:161], v222 offset:17408
	ds_read_b128 v[162:165], v222 offset:18432
	ds_read_b128 v[166:169], v222 offset:19456
	ds_read_b128 v[170:173], v222 offset:20480
	ds_read_b128 v[174:177], v222 offset:21504
	ds_read_b128 v[178:181], v222 offset:22528
	ds_read_b128 v[182:185], v222 offset:23552
	global_load_lds_dwordx4 v[238:239], off
	v_lshl_add_u64 v[240:241], s[28:29], 0, v[134:135]
	s_mov_b32 m0, s35
	s_nop 0
	global_load_lds_dwordx4 v[240:241], off
	s_barrier
	s_waitcnt lgkmcnt(0)
	v_mfma_f32_16x16x32_bf16 v[60:63], v[138:141], v[154:157], v[60:63]
	v_mfma_f32_16x16x32_bf16 v[56:59], v[146:149], v[154:157], v[56:59]
	v_mfma_f32_16x16x32_bf16 v[52:55], v[138:141], v[162:165], v[52:55]
	v_mfma_f32_16x16x32_bf16 v[48:51], v[146:149], v[162:165], v[48:51]
	v_mfma_f32_16x16x32_bf16 v[44:47], v[138:141], v[170:173], v[44:47]
	v_mfma_f32_16x16x32_bf16 v[40:43], v[146:149], v[170:173], v[40:43]
	v_mfma_f32_16x16x32_bf16 v[36:39], v[138:141], v[178:181], v[36:39]
	v_mfma_f32_16x16x32_bf16 v[32:35], v[146:149], v[178:181], v[32:35]
	v_mfma_f32_16x16x32_bf16 v[60:63], v[142:145], v[158:161], v[60:63]
	v_mfma_f32_16x16x32_bf16 v[56:59], v[150:153], v[158:161], v[56:59]
	v_mfma_f32_16x16x32_bf16 v[52:55], v[142:145], v[166:169], v[52:55]
	v_mfma_f32_16x16x32_bf16 v[48:51], v[150:153], v[166:169], v[48:51]
	v_mfma_f32_16x16x32_bf16 v[44:47], v[142:145], v[174:177], v[44:47]
	v_mfma_f32_16x16x32_bf16 v[40:43], v[150:153], v[174:177], v[40:43]
	v_mfma_f32_16x16x32_bf16 v[36:39], v[142:145], v[182:185], v[36:39]
	v_mfma_f32_16x16x32_bf16 v[32:35], v[150:153], v[182:185], v[32:35]
	s_barrier
; #define G_STAGE(bufoff, gbase, v0, v1) do { \
;     __builtin_amdgcn_global_load_lds((const unsigned*)((const char*)(gbase) + (v0)), (LAS unsigned*)(lds + (bufoff) + ldsw), 16, 0, 0); \
;     __builtin_amdgcn_global_load_lds((const unsigned*)((const char*)(gbase) + (v1)), (LAS unsigned*)(lds + (bufoff) + ldsw + 8192), 16, 0, 0); } while (0)
; #define G_LDA(dst, b, h) do { _Pragma("unroll") for (int m = 0; m < 4; ++m) _Pragma("unroll") for (int k = 0; k < 2; ++k) dst[m][k] = *(const LAS bf16x8*)(lds + G_SA(b, h) + aoff + m * 2048 + k * 1024); } while (0)
; #define G_LDB(dst, b, h) do { _Pragma("unroll") for (int n = 0; n < 2; ++n) _Pragma("unroll") for (int k = 0; k < 2; ++k) dst[n][k] = *(const LAS bf16x8*)(lds + G_SB(b, h) + boff + n * 2048 + k * 1024); } while (0)
; #define G_MMA(ai, bj, At, Bt) do { __builtin_amdgcn_s_setprio(1); _Pragma("unroll") for (int m = 0; m < 4; ++m) _Pragma("unroll") for (int n = 0; n < 2; ++n) _Pragma("unroll") for (int k = 0; k < 2; ++k) \
;     acc[ai][bj][m][n] = __builtin_amdgcn_mfma_f32_16x16x32_bf16(Bt[n][k], At[m][k], acc[ai][bj][m][n], 0, 0, 0); __builtin_amdgcn_s_setprio(0); } while (0)
; #define G_WAIT_V(n) asm volatile("s_waitcnt vmcnt(" #n ")" ::: "memory")
; #define G_WAIT_L(n) asm volatile("s_waitcnt lgkmcnt(" #n ")" ::: "memory")
; #define G_BAR __builtin_amdgcn_s_barrier()
; #define G_SCHED __builtin_amdgcn_sched_barrier(0)
; __device__ __forceinline__ void gemm_run(const Params& p, int l, int kind, int single) {
;     ...
;       G_STAGE(G_SB(0, 1), b2 + h2, w0, w1);
;       G_WAIT_V(6); G_BAR; G_MMA(1, 1, At, B1); G_BAR;
;       G_LDB(B0, 1, 0); G_SCHED; G_LDA(At, 1, 0); G_STAGE(G_SA(0, 1), a2 + h2, w0, w1);
;       G_WAIT_L(8); G_BAR; G_WAIT_L(0); G_MMA(0, 0, At, B0); G_BAR; G_SCHED;
;       G_LDB(B1, 1, 1); G_STAGE(G_SB(1, 0), b3, w0, w1);
;       G_BAR; G_WAIT_L(0); G_MMA(0, 1, At, B1); G_BAR;
;       G_LDA(At, 1, 1); G_STAGE(G_SA(1, 0), a3, w0, w1);
	s_add_u32 s26, s26, s24
	s_addc_u32 s27, s27, s25
	s_add_i32 s44, s45, s31
	v_lshl_add_u64 v[242:243], s[26:27], 0, v[136:137]
	s_mov_b32 m0, s44
	v_lshl_add_u64 v[244:245], s[26:27], 0, v[134:135]
	global_load_lds_dwordx4 v[242:243], off
	s_add_i32 m0, s44, 0x2000
	s_nop 0
	global_load_lds_dwordx4 v[244:245], off
	s_waitcnt vmcnt(6)
	s_barrier
	v_mfma_f32_16x16x32_bf16 v[28:31], v[204:207], v[154:157], v[28:31]
	v_mfma_f32_16x16x32_bf16 v[24:27], v[228:231], v[154:157], v[24:27]
	v_mfma_f32_16x16x32_bf16 v[20:23], v[204:207], v[162:165], v[20:23]
	v_mfma_f32_16x16x32_bf16 v[16:19], v[228:231], v[162:165], v[16:19]
	v_mfma_f32_16x16x32_bf16 v[12:15], v[204:207], v[170:173], v[12:15]
	v_mfma_f32_16x16x32_bf16 v[8:11], v[228:231], v[170:173], v[8:11]
	v_mfma_f32_16x16x32_bf16 v[4:7], v[204:207], v[178:181], v[4:7]
	v_mfma_f32_16x16x32_bf16 v[0:3], v[228:231], v[178:181], v[0:3]
	v_mfma_f32_16x16x32_bf16 v[28:31], v[224:227], v[158:161], v[28:31]
	v_mfma_f32_16x16x32_bf16 v[24:27], v[232:235], v[158:161], v[24:27]
	v_mfma_f32_16x16x32_bf16 v[20:23], v[224:227], v[166:169], v[20:23]
	v_mfma_f32_16x16x32_bf16 v[16:19], v[232:235], v[166:169], v[16:19]
	v_mfma_f32_16x16x32_bf16 v[12:15], v[224:227], v[174:177], v[12:15]
	v_mfma_f32_16x16x32_bf16 v[8:11], v[232:235], v[174:177], v[8:11]
	v_mfma_f32_16x16x32_bf16 v[4:7], v[224:227], v[182:185], v[4:7]
	v_mfma_f32_16x16x32_bf16 v[0:3], v[232:235], v[182:185], v[0:3]
	s_add_i32 s26, s91, 0x100
	v_add_u32_e32 v150, s26, v221
	s_barrier
	ds_read_b128 v[138:141], v150
	ds_read_b128 v[142:145], v150 offset:1024
	ds_read_b128 v[146:149], v150 offset:2048
	ds_read_b128 v[150:153], v150 offset:3072
	s_add_u32 s24, s28, s24
	s_addc_u32 s25, s29, s25
	s_mov_b32 m0, s36
	v_lshl_add_u64 v[136:137], s[24:25], 0, v[136:137]
	ds_read_b128 v[154:157], v222 offset:32768
	ds_read_b128 v[158:161], v222 offset:33792
	ds_read_b128 v[162:165], v222 offset:34816
	ds_read_b128 v[166:169], v222 offset:35840
	ds_read_b128 v[170:173], v222 offset:36864
	ds_read_b128 v[174:177], v222 offset:37888
	ds_read_b128 v[178:181], v222 offset:38912
	ds_read_b128 v[182:185], v222 offset:39936
	global_load_lds_dwordx4 v[136:137], off
	v_lshl_add_u64 v[134:135], s[24:25], 0, v[134:135]
	s_mov_b32 m0, s37
	s_nop 0
	global_load_lds_dwordx4 v[134:135], off
	s_waitcnt lgkmcnt(8)
	s_barrier
	s_waitcnt lgkmcnt(0)
	v_mfma_f32_16x16x32_bf16 v[124:127], v[138:141], v[154:157], v[124:127]
	v_mfma_f32_16x16x32_bf16 v[120:123], v[146:149], v[154:157], v[120:123]
	v_mfma_f32_16x16x32_bf16 v[116:119], v[138:141], v[162:165], v[116:119]
	v_mfma_f32_16x16x32_bf16 v[112:115], v[146:149], v[162:165], v[112:115]
	v_mfma_f32_16x16x32_bf16 v[108:111], v[138:141], v[170:173], v[108:111]
	v_mfma_f32_16x16x32_bf16 v[104:107], v[146:149], v[170:173], v[104:107]
	v_mfma_f32_16x16x32_bf16 v[100:103], v[138:141], v[178:181], v[100:103]
	v_mfma_f32_16x16x32_bf16 v[96:99], v[146:149], v[178:181], v[96:99]
	v_mfma_f32_16x16x32_bf16 v[124:127], v[142:145], v[158:161], v[124:127]
	v_mfma_f32_16x16x32_bf16 v[120:123], v[150:153], v[158:161], v[120:123]
	v_mfma_f32_16x16x32_bf16 v[116:119], v[142:145], v[166:169], v[116:119]
	v_mfma_f32_16x16x32_bf16 v[112:115], v[150:153], v[166:169], v[112:115]
	v_mfma_f32_16x16x32_bf16 v[108:111], v[142:145], v[174:177], v[108:111]
	v_mfma_f32_16x16x32_bf16 v[104:107], v[150:153], v[174:177], v[104:107]
	v_mfma_f32_16x16x32_bf16 v[100:103], v[142:145], v[182:185], v[100:103]
	v_mfma_f32_16x16x32_bf16 v[96:99], v[150:153], v[182:185], v[96:99]
	s_barrier
	s_add_i32 s24, s94, 0x100
	s_add_i32 s25, s26, s31
	v_add_u32_e32 v223, s24, v221
	v_lshl_add_u64 v[186:187], v[186:187], 0, s[96:97]
	s_mov_b32 m0, s25
	ds_read_b128 v[134:137], v223
	ds_read_b128 v[204:207], v223 offset:1024
	ds_read_b128 v[224:227], v223 offset:2048
	ds_read_b128 v[228:231], v223 offset:3072
	global_load_lds_dwordx4 v[186:187], off
	v_lshl_add_u64 v[186:187], v[236:237], 0, s[96:97]
	s_add_i32 m0, s25, 0x2000
	s_nop 0
	global_load_lds_dwordx4 v[186:187], off
	s_barrier
; #define G_STAGE(bufoff, gbase, v0, v1) do { \
;     __builtin_amdgcn_global_load_lds((const unsigned*)((const char*)(gbase) + (v0)), (LAS unsigned*)(lds + (bufoff) + ldsw), 16, 0, 0); \
;     __builtin_amdgcn_global_load_lds((const unsigned*)((const char*)(gbase) + (v1)), (LAS unsigned*)(lds + (bufoff) + ldsw + 8192), 16, 0, 0); } while (0)
; #define G_MMA(ai, bj, At, Bt) do { __builtin_amdgcn_s_setprio(1); _Pragma("unroll") for (int m = 0; m < 4; ++m) _Pragma("unroll") for (int n = 0; n < 2; ++n) _Pragma("unroll") for (int k = 0; k < 2; ++k) \
;     acc[ai][bj][m][n] = __builtin_amdgcn_mfma_f32_16x16x32_bf16(Bt[n][k], At[m][k], acc[ai][bj][m][n], 0, 0, 0); __builtin_amdgcn_s_setprio(0); } while (0)
; #define G_WAIT_V(n) asm volatile("s_waitcnt vmcnt(" #n ")" ::: "memory")
; #define G_WAIT_L(n) asm volatile("s_waitcnt lgkmcnt(" #n ")" ::: "memory")
; #define G_BAR __builtin_amdgcn_s_barrier()
; #define G_SCHED __builtin_amdgcn_sched_barrier(0)
; __device__ __forceinline__ void gemm_run(const Params& p, int l, int kind, int single) {
;     ...
;       G_BAR; G_WAIT_L(0); G_MMA(1, 0, At, B0); G_BAR; G_SCHED;
;       G_STAGE(G_SB(1, 1), b3 + h2, w0, w1);
;       G_WAIT_V(6); G_BAR; G_MMA(1, 1, At, B1); G_BAR;
	s_waitcnt lgkmcnt(0)
	v_mfma_f32_16x16x32_bf16 v[92:95], v[134:137], v[154:157], v[92:95]
	v_mfma_f32_16x16x32_bf16 v[88:91], v[224:227], v[154:157], v[88:91]
	v_mfma_f32_16x16x32_bf16 v[84:87], v[134:137], v[162:165], v[84:87]
	v_mfma_f32_16x16x32_bf16 v[80:83], v[224:227], v[162:165], v[80:83]
	v_mfma_f32_16x16x32_bf16 v[76:79], v[134:137], v[170:173], v[76:79]
	v_mfma_f32_16x16x32_bf16 v[72:75], v[224:227], v[170:173], v[72:75]
	v_mfma_f32_16x16x32_bf16 v[68:71], v[134:137], v[178:181], v[68:71]
	v_mfma_f32_16x16x32_bf16 v[64:67], v[224:227], v[178:181], v[64:67]
	v_mfma_f32_16x16x32_bf16 v[92:95], v[204:207], v[158:161], v[92:95]
	v_mfma_f32_16x16x32_bf16 v[88:91], v[228:231], v[158:161], v[88:91]
	v_mfma_f32_16x16x32_bf16 v[84:87], v[204:207], v[166:169], v[84:87]
	v_mfma_f32_16x16x32_bf16 v[80:83], v[228:231], v[166:169], v[80:83]
	v_mfma_f32_16x16x32_bf16 v[76:79], v[204:207], v[174:177], v[76:79]
	v_mfma_f32_16x16x32_bf16 v[72:75], v[228:231], v[174:177], v[72:75]
	v_mfma_f32_16x16x32_bf16 v[68:71], v[204:207], v[182:185], v[68:71]
	v_mfma_f32_16x16x32_bf16 v[64:67], v[228:231], v[182:185], v[64:67]
	s_mov_b32 m0, s38
	v_lshl_add_u64 v[186:187], v[238:239], 0, s[96:97]
	s_barrier
	ds_read_b128 v[154:157], v222 offset:49152
	ds_read_b128 v[158:161], v222 offset:50176
	ds_read_b128 v[162:165], v222 offset:51200
	ds_read_b128 v[166:169], v222 offset:52224
	ds_read_b128 v[170:173], v222 offset:53248
	ds_read_b128 v[174:177], v222 offset:54272
	ds_read_b128 v[178:181], v222 offset:55296
	ds_read_b128 v[182:185], v222 offset:56320
	global_load_lds_dwordx4 v[186:187], off
	v_lshl_add_u64 v[186:187], v[240:241], 0, s[96:97]
	s_mov_b32 m0, s39
	s_nop 0
	global_load_lds_dwordx4 v[186:187], off
	s_barrier
	s_waitcnt lgkmcnt(0)
	v_mfma_f32_16x16x32_bf16 v[60:63], v[138:141], v[154:157], v[60:63]
	v_mfma_f32_16x16x32_bf16 v[56:59], v[146:149], v[154:157], v[56:59]
	v_mfma_f32_16x16x32_bf16 v[52:55], v[138:141], v[162:165], v[52:55]
	v_mfma_f32_16x16x32_bf16 v[48:51], v[146:149], v[162:165], v[48:51]
	v_mfma_f32_16x16x32_bf16 v[44:47], v[138:141], v[170:173], v[44:47]
	v_mfma_f32_16x16x32_bf16 v[40:43], v[146:149], v[170:173], v[40:43]
	v_mfma_f32_16x16x32_bf16 v[36:39], v[138:141], v[178:181], v[36:39]
	v_mfma_f32_16x16x32_bf16 v[32:35], v[146:149], v[178:181], v[32:35]
	v_mfma_f32_16x16x32_bf16 v[60:63], v[142:145], v[158:161], v[60:63]
	v_mfma_f32_16x16x32_bf16 v[56:59], v[150:153], v[158:161], v[56:59]
	v_mfma_f32_16x16x32_bf16 v[52:55], v[142:145], v[166:169], v[52:55]
	v_mfma_f32_16x16x32_bf16 v[48:51], v[150:153], v[166:169], v[48:51]
	v_mfma_f32_16x16x32_bf16 v[44:47], v[142:145], v[174:177], v[44:47]
	v_mfma_f32_16x16x32_bf16 v[40:43], v[150:153], v[174:177], v[40:43]
	v_mfma_f32_16x16x32_bf16 v[36:39], v[142:145], v[182:185], v[36:39]
	v_mfma_f32_16x16x32_bf16 v[32:35], v[150:153], v[182:185], v[32:35]
	s_barrier
	s_add_i32 s24, s24, s31
	v_lshl_add_u64 v[138:139], v[242:243], 0, s[96:97]
	s_mov_b32 m0, s24
	s_nop 0
	global_load_lds_dwordx4 v[138:139], off
	v_lshl_add_u64 v[138:139], v[244:245], 0, s[96:97]
	s_add_i32 m0, s24, 0x2000
	s_nop 0
	global_load_lds_dwordx4 v[138:139], off
	s_waitcnt vmcnt(6)
	s_barrier
	v_mfma_f32_16x16x32_bf16 v[28:31], v[134:137], v[154:157], v[28:31]
	v_mfma_f32_16x16x32_bf16 v[24:27], v[224:227], v[154:157], v[24:27]
	v_mfma_f32_16x16x32_bf16 v[20:23], v[134:137], v[162:165], v[20:23]
	v_mfma_f32_16x16x32_bf16 v[16:19], v[224:227], v[162:165], v[16:19]
	v_mfma_f32_16x16x32_bf16 v[12:15], v[134:137], v[170:173], v[12:15]
	v_mfma_f32_16x16x32_bf16 v[8:11], v[224:227], v[170:173], v[8:11]
	v_mfma_f32_16x16x32_bf16 v[4:7], v[134:137], v[178:181], v[4:7]
	v_mfma_f32_16x16x32_bf16 v[0:3], v[224:227], v[178:181], v[0:3]
	v_mfma_f32_16x16x32_bf16 v[28:31], v[204:207], v[158:161], v[28:31]
	v_mfma_f32_16x16x32_bf16 v[24:27], v[228:231], v[158:161], v[24:27]
	v_mfma_f32_16x16x32_bf16 v[20:23], v[204:207], v[166:169], v[20:23]
	v_mfma_f32_16x16x32_bf16 v[16:19], v[228:231], v[166:169], v[16:19]
	v_mfma_f32_16x16x32_bf16 v[12:15], v[204:207], v[174:177], v[12:15]
	v_mfma_f32_16x16x32_bf16 v[8:11], v[228:231], v[174:177], v[8:11]
	v_mfma_f32_16x16x32_bf16 v[4:7], v[204:207], v[182:185], v[4:7]
	v_mfma_f32_16x16x32_bf16 v[0:3], v[228:231], v[182:185], v[0:3]
	s_add_u32 s12, s12, 0x100
	s_addc_u32 s13, s13, 0
	s_add_u32 s22, s22, 0x100
	s_addc_u32 s23, s23, 0
	s_cmp_ge_i32 s15, s2
	s_barrier
	s_cbranch_scc1 .LBB0_910

; #define G_STAGE(bufoff, gbase, v0, v1) do { \
;     __builtin_amdgcn_global_load_lds((const unsigned*)((const char*)(gbase) + (v0)), (LAS unsigned*)(lds + (bufoff) + ldsw), 16, 0, 0); \
;     __builtin_amdgcn_global_load_lds((const unsigned*)((const char*)(gbase) + (v1)), (LAS unsigned*)(lds + (bufoff) + ldsw + 8192), 16, 0, 0); } while (0)
; #define G_LDA(dst, b, h) do { _Pragma("unroll") for (int m = 0; m < 4; ++m) _Pragma("unroll") for (int k = 0; k < 2; ++k) dst[m][k] = *(const LAS bf16x8*)(lds + G_SA(b, h) + aoff + m * 2048 + k * 1024); } while (0)
; #define G_LDB(dst, b, h) do { _Pragma("unroll") for (int n = 0; n < 2; ++n) _Pragma("unroll") for (int k = 0; k < 2; ++k) dst[n][k] = *(const LAS bf16x8*)(lds + G_SB(b, h) + boff + n * 2048 + k * 1024); } while (0)
; #define G_MMA(ai, bj, At, Bt) do { __builtin_amdgcn_s_setprio(1); _Pragma("unroll") for (int m = 0; m < 4; ++m) _Pragma("unroll") for (int n = 0; n < 2; ++n) _Pragma("unroll") for (int k = 0; k < 2; ++k) \
;     acc[ai][bj][m][n] = __builtin_amdgcn_mfma_f32_16x16x32_bf16(Bt[n][k], At[m][k], acc[ai][bj][m][n], 0, 0, 0); __builtin_amdgcn_s_setprio(0); } while (0)
; #define G_WAIT_L(n) asm volatile("s_waitcnt lgkmcnt(" #n ")" ::: "memory")
; #define G_BAR __builtin_amdgcn_s_barrier()
; #define G_SCHED __builtin_amdgcn_sched_barrier(0)
; __device__ __forceinline__ void gemm_run(const Params& p, int l, int kind, int single) {
;     ...
;       G_LDB(B0, 0, 0); G_SCHED; G_LDA(At, 0, 0); G_STAGE(G_SA(1, 1), a1 + hc, vc0, vc1);
;       G_WAIT_L(8); G_BAR; G_WAIT_L(0); G_MMA(0, 0, At, B0); G_BAR; G_SCHED;
;       G_LDB(B1, 0, 1); G_STAGE(G_SB(0, 0), b2, w0, w1);
;       G_BAR; G_WAIT_L(0); G_MMA(0, 1, At, B1); G_BAR;
;       G_LDA(At, 0, 1); G_STAGE(G_SA(0, 0), a2, w0, w1);
;       G_BAR; G_WAIT_L(0); G_MMA(1, 0, At, B0); G_BAR; G_SCHED;
.LBB0_1012:
	s_add_u32 s14, s12, 0xfffc0080
	s_addc_u32 s15, s13, -1
	s_cmp_eq_u32 s27, 12
	s_cselect_b32 s17, s9, s15
	s_cselect_b32 s16, s8, s14
	s_cselect_b32 s15, s11, s5
	s_cselect_b32 s14, s10, s1
	s_add_i32 s28, s89, 0x100
	v_add_u32_e32 v138, s28, v140
	ds_read_b128 v[134:137], v138
	ds_read_b128 v[142:145], v138 offset:1024
	ds_read_b128 v[146:149], v138 offset:2048
	ds_read_b128 v[150:153], v138 offset:3072
	v_lshl_add_u64 v[138:139], s[12:13], 0, v[130:131]
	s_add_i32 m0, s18, 0xc000
	ds_read_b128 v[154:157], v141
	ds_read_b128 v[158:161], v141 offset:1024
	ds_read_b128 v[162:165], v141 offset:2048
	ds_read_b128 v[166:169], v141 offset:3072
	ds_read_b128 v[170:173], v141 offset:4096
	ds_read_b128 v[174:177], v141 offset:5120
	ds_read_b128 v[178:181], v141 offset:6144
	ds_read_b128 v[182:185], v141 offset:7168
	global_load_lds_dwordx4 v[138:139], off
	v_lshl_add_u64 v[138:139], s[12:13], 0, v[132:133]
	s_add_i32 m0, s18, 0xe000
	s_nop 0
	global_load_lds_dwordx4 v[138:139], off
	s_waitcnt lgkmcnt(8)
	s_barrier
	s_waitcnt lgkmcnt(0)
	v_mfma_f32_16x16x32_bf16 v[124:127], v[134:137], v[154:157], v[124:127]
	v_mfma_f32_16x16x32_bf16 v[120:123], v[146:149], v[154:157], v[120:123]
	v_mfma_f32_16x16x32_bf16 v[116:119], v[134:137], v[162:165], v[116:119]
	v_mfma_f32_16x16x32_bf16 v[112:115], v[146:149], v[162:165], v[112:115]
	v_mfma_f32_16x16x32_bf16 v[108:111], v[134:137], v[170:173], v[108:111]
	v_mfma_f32_16x16x32_bf16 v[100:103], v[146:149], v[170:173], v[100:103]
	v_mfma_f32_16x16x32_bf16 v[84:87], v[134:137], v[178:181], v[84:87]
	v_mfma_f32_16x16x32_bf16 v[72:75], v[146:149], v[178:181], v[72:75]
	v_mfma_f32_16x16x32_bf16 v[124:127], v[142:145], v[158:161], v[124:127]
	v_mfma_f32_16x16x32_bf16 v[120:123], v[150:153], v[158:161], v[120:123]
	v_mfma_f32_16x16x32_bf16 v[116:119], v[142:145], v[166:169], v[116:119]
	v_mfma_f32_16x16x32_bf16 v[112:115], v[150:153], v[166:169], v[112:115]
	v_mfma_f32_16x16x32_bf16 v[108:111], v[142:145], v[174:177], v[108:111]
	v_mfma_f32_16x16x32_bf16 v[100:103], v[150:153], v[174:177], v[100:103]
	v_mfma_f32_16x16x32_bf16 v[84:87], v[142:145], v[182:185], v[84:87]
	v_mfma_f32_16x16x32_bf16 v[72:75], v[150:153], v[182:185], v[72:75]
	s_barrier
	s_add_i32 s30, s90, 0x100
	v_add_u32_e32 v138, s30, v140
	s_add_i32 s28, s28, s3
	ds_read_b128 v[200:203], v138
	ds_read_b128 v[204:207], v138 offset:1024
	ds_read_b128 v[218:221], v138 offset:2048
	ds_read_b128 v[222:225], v138 offset:3072
	v_lshl_add_u64 v[138:139], s[14:15], 0, v[190:191]
	s_mov_b32 m0, s28
	v_lshl_add_u64 v[186:187], s[14:15], 0, v[128:129]
	global_load_lds_dwordx4 v[138:139], off
	s_add_i32 m0, s28, 0x2000
	s_nop 0
	global_load_lds_dwordx4 v[186:187], off
	s_barrier
	s_waitcnt lgkmcnt(0)
	v_mfma_f32_16x16x32_bf16 v[104:107], v[200:203], v[154:157], v[104:107]
	v_mfma_f32_16x16x32_bf16 v[96:99], v[218:221], v[154:157], v[96:99]
	v_mfma_f32_16x16x32_bf16 v[92:95], v[200:203], v[162:165], v[92:95]
	v_mfma_f32_16x16x32_bf16 v[88:91], v[218:221], v[162:165], v[88:91]
	v_mfma_f32_16x16x32_bf16 v[80:83], v[200:203], v[170:173], v[80:83]
	v_mfma_f32_16x16x32_bf16 v[76:79], v[218:221], v[170:173], v[76:79]
	v_mfma_f32_16x16x32_bf16 v[68:71], v[200:203], v[178:181], v[68:71]
	v_mfma_f32_16x16x32_bf16 v[64:67], v[218:221], v[178:181], v[64:67]
	v_mfma_f32_16x16x32_bf16 v[104:107], v[204:207], v[158:161], v[104:107]
	v_mfma_f32_16x16x32_bf16 v[96:99], v[222:225], v[158:161], v[96:99]
	v_mfma_f32_16x16x32_bf16 v[92:95], v[204:207], v[166:169], v[92:95]
	v_mfma_f32_16x16x32_bf16 v[88:91], v[222:225], v[166:169], v[88:91]
	v_mfma_f32_16x16x32_bf16 v[80:83], v[204:207], v[174:177], v[80:83]
	v_mfma_f32_16x16x32_bf16 v[76:79], v[222:225], v[174:177], v[76:79]
	v_mfma_f32_16x16x32_bf16 v[68:71], v[204:207], v[182:185], v[68:71]
	v_mfma_f32_16x16x32_bf16 v[64:67], v[222:225], v[182:185], v[64:67]
	s_mov_b32 m0, s18
	v_lshl_add_u64 v[226:227], s[16:17], 0, v[190:191]
	s_barrier
	ds_read_b128 v[154:157], v141 offset:16384
	ds_read_b128 v[158:161], v141 offset:17408
	ds_read_b128 v[162:165], v141 offset:18432
	ds_read_b128 v[166:169], v141 offset:19456
	ds_read_b128 v[170:173], v141 offset:20480
	ds_read_b128 v[174:177], v141 offset:21504
	ds_read_b128 v[178:181], v141 offset:22528
	ds_read_b128 v[182:185], v141 offset:23552
	global_load_lds_dwordx4 v[226:227], off
	v_lshl_add_u64 v[228:229], s[16:17], 0, v[128:129]
	s_mov_b32 m0, s19
	s_nop 0
	global_load_lds_dwordx4 v[228:229], off
	s_barrier
	s_waitcnt lgkmcnt(0)
	v_mfma_f32_16x16x32_bf16 v[60:63], v[134:137], v[154:157], v[60:63]
	v_mfma_f32_16x16x32_bf16 v[56:59], v[146:149], v[154:157], v[56:59]
	v_mfma_f32_16x16x32_bf16 v[52:55], v[134:137], v[162:165], v[52:55]
	v_mfma_f32_16x16x32_bf16 v[48:51], v[146:149], v[162:165], v[48:51]
	v_mfma_f32_16x16x32_bf16 v[44:47], v[134:137], v[170:173], v[44:47]
	v_mfma_f32_16x16x32_bf16 v[36:39], v[146:149], v[170:173], v[36:39]
	v_mfma_f32_16x16x32_bf16 v[28:31], v[134:137], v[178:181], v[28:31]
	v_mfma_f32_16x16x32_bf16 v[16:19], v[146:149], v[178:181], v[16:19]
	v_mfma_f32_16x16x32_bf16 v[60:63], v[142:145], v[158:161], v[60:63]
	v_mfma_f32_16x16x32_bf16 v[56:59], v[150:153], v[158:161], v[56:59]
	v_mfma_f32_16x16x32_bf16 v[52:55], v[142:145], v[166:169], v[52:55]
	v_mfma_f32_16x16x32_bf16 v[48:51], v[150:153], v[166:169], v[48:51]
	v_mfma_f32_16x16x32_bf16 v[44:47], v[142:145], v[174:177], v[44:47]
	v_mfma_f32_16x16x32_bf16 v[36:39], v[150:153], v[174:177], v[36:39]
	v_mfma_f32_16x16x32_bf16 v[28:31], v[142:145], v[182:185], v[28:31]
	v_mfma_f32_16x16x32_bf16 v[16:19], v[150:153], v[182:185], v[16:19]
	s_barrier
; #define G_STAGE(bufoff, gbase, v0, v1) do { \
;     __builtin_amdgcn_global_load_lds((const unsigned*)((const char*)(gbase) + (v0)), (LAS unsigned*)(lds + (bufoff) + ldsw), 16, 0, 0); \
;     __builtin_amdgcn_global_load_lds((const unsigned*)((const char*)(gbase) + (v1)), (LAS unsigned*)(lds + (bufoff) + ldsw + 8192), 16, 0, 0); } while (0)
; #define G_LDA(dst, b, h) do { _Pragma("unroll") for (int m = 0; m < 4; ++m) _Pragma("unroll") for (int k = 0; k < 2; ++k) dst[m][k] = *(const LAS bf16x8*)(lds + G_SA(b, h) + aoff + m * 2048 + k * 1024); } while (0)
; #define G_LDB(dst, b, h) do { _Pragma("unroll") for (int n = 0; n < 2; ++n) _Pragma("unroll") for (int k = 0; k < 2; ++k) dst[n][k] = *(const LAS bf16x8*)(lds + G_SB(b, h) + boff + n * 2048 + k * 1024); } while (0)
; #define G_MMA(ai, bj, At, Bt) do { __builtin_amdgcn_s_setprio(1); _Pragma("unroll") for (int m = 0; m < 4; ++m) _Pragma("unroll") for (int n = 0; n < 2; ++n) _Pragma("unroll") for (int k = 0; k < 2; ++k) \
;     acc[ai][bj][m][n] = __builtin_amdgcn_mfma_f32_16x16x32_bf16(Bt[n][k], At[m][k], acc[ai][bj][m][n], 0, 0, 0); __builtin_amdgcn_s_setprio(0); } while (0)
; #define G_WAIT_V(n) asm volatile("s_waitcnt vmcnt(" #n ")" ::: "memory")
; #define G_WAIT_L(n) asm volatile("s_waitcnt lgkmcnt(" #n ")" ::: "memory")
; #define G_BAR __builtin_amdgcn_s_barrier()
; #define G_SCHED __builtin_amdgcn_sched_barrier(0)
; __device__ __forceinline__ void gemm_run(const Params& p, int l, int kind, int single) {
;     ...
;       G_STAGE(G_SB(0, 1), b2 + h2, w0, w1);
;       G_WAIT_V(6); G_BAR; G_MMA(1, 1, At, B1); G_BAR;
;       G_LDB(B0, 1, 0); G_SCHED; G_LDA(At, 1, 0); G_STAGE(G_SA(0, 1), a2 + h2, w0, w1);
;       G_WAIT_L(8); G_BAR; G_WAIT_L(0); G_MMA(0, 0, At, B0); G_BAR; G_SCHED;
;       G_LDB(B1, 1, 1); G_STAGE(G_SB(1, 0), b3, w0, w1);
;       G_BAR; G_WAIT_L(0); G_MMA(0, 1, At, B1); G_BAR;
;       G_LDA(At, 1, 1); G_STAGE(G_SA(1, 0), a3, w0, w1);
	s_add_u32 s28, s14, 0x40000
	s_addc_u32 s29, s15, 0
	s_add_i32 s30, s30, s3
	v_lshl_add_u64 v[134:135], s[28:29], 0, v[190:191]
	s_mov_b32 m0, s30
	s_nop 0
	global_load_lds_dwordx4 v[134:135], off
	v_lshl_add_u64 v[134:135], s[28:29], 0, v[128:129]
	s_add_i32 m0, s30, 0x2000
	s_nop 0
	global_load_lds_dwordx4 v[134:135], off
	s_waitcnt vmcnt(6)
	s_barrier
	v_mfma_f32_16x16x32_bf16 v[40:43], v[200:203], v[154:157], v[40:43]
	v_mfma_f32_16x16x32_bf16 v[32:35], v[218:221], v[154:157], v[32:35]
	v_mfma_f32_16x16x32_bf16 v[24:27], v[200:203], v[162:165], v[24:27]
	v_mfma_f32_16x16x32_bf16 v[20:23], v[218:221], v[162:165], v[20:23]
	v_mfma_f32_16x16x32_bf16 v[12:15], v[200:203], v[170:173], v[12:15]
	v_mfma_f32_16x16x32_bf16 v[8:11], v[218:221], v[170:173], v[8:11]
	v_mfma_f32_16x16x32_bf16 v[4:7], v[200:203], v[178:181], v[4:7]
	v_mfma_f32_16x16x32_bf16 v[0:3], v[218:221], v[178:181], v[0:3]
	v_mfma_f32_16x16x32_bf16 v[40:43], v[204:207], v[158:161], v[40:43]
	v_mfma_f32_16x16x32_bf16 v[32:35], v[222:225], v[158:161], v[32:35]
	v_mfma_f32_16x16x32_bf16 v[24:27], v[204:207], v[166:169], v[24:27]
	v_mfma_f32_16x16x32_bf16 v[20:23], v[222:225], v[166:169], v[20:23]
	v_mfma_f32_16x16x32_bf16 v[12:15], v[204:207], v[174:177], v[12:15]
	v_mfma_f32_16x16x32_bf16 v[8:11], v[222:225], v[174:177], v[8:11]
	v_mfma_f32_16x16x32_bf16 v[4:7], v[204:207], v[182:185], v[4:7]
	v_mfma_f32_16x16x32_bf16 v[0:3], v[222:225], v[182:185], v[0:3]
	s_add_i32 s28, s91, 0x100
	v_add_u32_e32 v150, s28, v140
	s_barrier
	ds_read_b128 v[134:137], v150
	ds_read_b128 v[142:145], v150 offset:1024
	ds_read_b128 v[146:149], v150 offset:2048
	ds_read_b128 v[150:153], v150 offset:3072
	s_add_u32 s16, s16, 0x40000
	s_addc_u32 s17, s17, 0
	s_mov_b32 m0, s20
	v_lshl_add_u64 v[200:201], s[16:17], 0, v[190:191]
	ds_read_b128 v[154:157], v141 offset:32768
	ds_read_b128 v[158:161], v141 offset:33792
	ds_read_b128 v[162:165], v141 offset:34816
	ds_read_b128 v[166:169], v141 offset:35840
	ds_read_b128 v[170:173], v141 offset:36864
	ds_read_b128 v[174:177], v141 offset:37888
	ds_read_b128 v[178:181], v141 offset:38912
	ds_read_b128 v[182:185], v141 offset:39936
	global_load_lds_dwordx4 v[200:201], off
	v_lshl_add_u64 v[200:201], s[16:17], 0, v[128:129]
	s_mov_b32 m0, s21
	s_nop 0
	global_load_lds_dwordx4 v[200:201], off
	s_waitcnt lgkmcnt(8)
	s_barrier
	s_waitcnt lgkmcnt(0)
	v_mfma_f32_16x16x32_bf16 v[124:127], v[134:137], v[154:157], v[124:127]
	v_mfma_f32_16x16x32_bf16 v[120:123], v[146:149], v[154:157], v[120:123]
	v_mfma_f32_16x16x32_bf16 v[116:119], v[134:137], v[162:165], v[116:119]
	v_mfma_f32_16x16x32_bf16 v[112:115], v[146:149], v[162:165], v[112:115]
	v_mfma_f32_16x16x32_bf16 v[108:111], v[134:137], v[170:173], v[108:111]
	v_mfma_f32_16x16x32_bf16 v[100:103], v[146:149], v[170:173], v[100:103]
	v_mfma_f32_16x16x32_bf16 v[84:87], v[134:137], v[178:181], v[84:87]
	v_mfma_f32_16x16x32_bf16 v[72:75], v[146:149], v[178:181], v[72:75]
	v_mfma_f32_16x16x32_bf16 v[124:127], v[142:145], v[158:161], v[124:127]
	v_mfma_f32_16x16x32_bf16 v[120:123], v[150:153], v[158:161], v[120:123]
	v_mfma_f32_16x16x32_bf16 v[116:119], v[142:145], v[166:169], v[116:119]
	v_mfma_f32_16x16x32_bf16 v[112:115], v[150:153], v[166:169], v[112:115]
	v_mfma_f32_16x16x32_bf16 v[108:111], v[142:145], v[174:177], v[108:111]
	v_mfma_f32_16x16x32_bf16 v[100:103], v[150:153], v[174:177], v[100:103]
	v_mfma_f32_16x16x32_bf16 v[84:87], v[142:145], v[182:185], v[84:87]
	v_mfma_f32_16x16x32_bf16 v[72:75], v[150:153], v[182:185], v[72:75]
	s_barrier
	s_add_i32 s16, s94, 0x100
	s_add_i32 s17, s28, s3
	v_add_u32_e32 v199, s16, v140
	v_lshl_add_u64 v[138:139], v[138:139], 0, s[96:97]
	s_mov_b32 m0, s17
	ds_read_b128 v[200:203], v199
	ds_read_b128 v[204:207], v199 offset:1024
	ds_read_b128 v[218:221], v199 offset:2048
	ds_read_b128 v[222:225], v199 offset:3072
	global_load_lds_dwordx4 v[138:139], off
	v_lshl_add_u64 v[138:139], v[186:187], 0, s[96:97]
	s_add_i32 m0, s17, 0x2000
	s_nop 0
	global_load_lds_dwordx4 v[138:139], off
	s_barrier
; #define G_STAGE(bufoff, gbase, v0, v1) do { \
;     __builtin_amdgcn_global_load_lds((const unsigned*)((const char*)(gbase) + (v0)), (LAS unsigned*)(lds + (bufoff) + ldsw), 16, 0, 0); \
;     __builtin_amdgcn_global_load_lds((const unsigned*)((const char*)(gbase) + (v1)), (LAS unsigned*)(lds + (bufoff) + ldsw + 8192), 16, 0, 0); } while (0)
; #define G_MMA(ai, bj, At, Bt) do { __builtin_amdgcn_s_setprio(1); _Pragma("unroll") for (int m = 0; m < 4; ++m) _Pragma("unroll") for (int n = 0; n < 2; ++n) _Pragma("unroll") for (int k = 0; k < 2; ++k) \
;     acc[ai][bj][m][n] = __builtin_amdgcn_mfma_f32_16x16x32_bf16(Bt[n][k], At[m][k], acc[ai][bj][m][n], 0, 0, 0); __builtin_amdgcn_s_setprio(0); } while (0)
; #define G_WAIT_V(n) asm volatile("s_waitcnt vmcnt(" #n ")" ::: "memory")
; #define G_WAIT_L(n) asm volatile("s_waitcnt lgkmcnt(" #n ")" ::: "memory")
; #define G_BAR __builtin_amdgcn_s_barrier()
; #define G_SCHED __builtin_amdgcn_sched_barrier(0)
; __device__ __forceinline__ void gemm_run(const Params& p, int l, int kind, int single) {
;     ...
;       G_BAR; G_WAIT_L(0); G_MMA(1, 0, At, B0); G_BAR; G_SCHED;
;       G_STAGE(G_SB(1, 1), b3 + h2, w0, w1);
;       G_WAIT_V(6); G_BAR; G_MMA(1, 1, At, B1); G_BAR;
	s_waitcnt lgkmcnt(0)
	v_mfma_f32_16x16x32_bf16 v[104:107], v[200:203], v[154:157], v[104:107]
	v_mfma_f32_16x16x32_bf16 v[96:99], v[218:221], v[154:157], v[96:99]
	v_mfma_f32_16x16x32_bf16 v[92:95], v[200:203], v[162:165], v[92:95]
	v_mfma_f32_16x16x32_bf16 v[88:91], v[218:221], v[162:165], v[88:91]
	v_mfma_f32_16x16x32_bf16 v[80:83], v[200:203], v[170:173], v[80:83]
	v_mfma_f32_16x16x32_bf16 v[76:79], v[218:221], v[170:173], v[76:79]
	v_mfma_f32_16x16x32_bf16 v[68:71], v[200:203], v[178:181], v[68:71]
	v_mfma_f32_16x16x32_bf16 v[64:67], v[218:221], v[178:181], v[64:67]
	v_mfma_f32_16x16x32_bf16 v[104:107], v[204:207], v[158:161], v[104:107]
	v_mfma_f32_16x16x32_bf16 v[96:99], v[222:225], v[158:161], v[96:99]
	v_mfma_f32_16x16x32_bf16 v[92:95], v[204:207], v[166:169], v[92:95]
	v_mfma_f32_16x16x32_bf16 v[88:91], v[222:225], v[166:169], v[88:91]
	v_mfma_f32_16x16x32_bf16 v[80:83], v[204:207], v[174:177], v[80:83]
	v_mfma_f32_16x16x32_bf16 v[76:79], v[222:225], v[174:177], v[76:79]
	v_mfma_f32_16x16x32_bf16 v[68:71], v[204:207], v[182:185], v[68:71]
	v_mfma_f32_16x16x32_bf16 v[64:67], v[222:225], v[182:185], v[64:67]
	s_mov_b32 m0, s22
	v_lshl_add_u64 v[138:139], v[226:227], 0, s[96:97]
	s_barrier
	ds_read_b128 v[154:157], v141 offset:49152
	ds_read_b128 v[158:161], v141 offset:50176
	ds_read_b128 v[162:165], v141 offset:51200
	ds_read_b128 v[166:169], v141 offset:52224
	ds_read_b128 v[170:173], v141 offset:53248
	ds_read_b128 v[174:177], v141 offset:54272
	ds_read_b128 v[178:181], v141 offset:55296
	ds_read_b128 v[182:185], v141 offset:56320
	global_load_lds_dwordx4 v[138:139], off
	v_lshl_add_u64 v[138:139], v[228:229], 0, s[96:97]
	s_mov_b32 m0, s23
	s_nop 0
	global_load_lds_dwordx4 v[138:139], off
	s_barrier
	s_waitcnt lgkmcnt(0)
	v_mfma_f32_16x16x32_bf16 v[60:63], v[134:137], v[154:157], v[60:63]
	v_mfma_f32_16x16x32_bf16 v[56:59], v[146:149], v[154:157], v[56:59]
	v_mfma_f32_16x16x32_bf16 v[52:55], v[134:137], v[162:165], v[52:55]
	v_mfma_f32_16x16x32_bf16 v[48:51], v[146:149], v[162:165], v[48:51]
	v_mfma_f32_16x16x32_bf16 v[44:47], v[134:137], v[170:173], v[44:47]
	v_mfma_f32_16x16x32_bf16 v[36:39], v[146:149], v[170:173], v[36:39]
	v_mfma_f32_16x16x32_bf16 v[28:31], v[134:137], v[178:181], v[28:31]
	v_mfma_f32_16x16x32_bf16 v[16:19], v[146:149], v[178:181], v[16:19]
	v_mfma_f32_16x16x32_bf16 v[60:63], v[142:145], v[158:161], v[60:63]
	v_mfma_f32_16x16x32_bf16 v[56:59], v[150:153], v[158:161], v[56:59]
	v_mfma_f32_16x16x32_bf16 v[52:55], v[142:145], v[166:169], v[52:55]
	v_mfma_f32_16x16x32_bf16 v[48:51], v[150:153], v[166:169], v[48:51]
	v_mfma_f32_16x16x32_bf16 v[44:47], v[142:145], v[174:177], v[44:47]
	v_mfma_f32_16x16x32_bf16 v[36:39], v[150:153], v[174:177], v[36:39]
	v_mfma_f32_16x16x32_bf16 v[28:31], v[142:145], v[182:185], v[28:31]
	v_mfma_f32_16x16x32_bf16 v[16:19], v[150:153], v[182:185], v[16:19]
	s_barrier
	s_add_u32 s14, s14, 0x40080
	s_addc_u32 s15, s15, 0
	s_add_i32 s16, s16, s3
	v_lshl_add_u64 v[134:135], s[14:15], 0, v[190:191]
	s_mov_b32 m0, s16
	s_nop 0
	global_load_lds_dwordx4 v[134:135], off
	v_lshl_add_u64 v[134:135], s[14:15], 0, v[128:129]
	s_add_i32 m0, s16, 0x2000
	s_nop 0
	global_load_lds_dwordx4 v[134:135], off
	s_waitcnt vmcnt(6)
	s_barrier
	v_mfma_f32_16x16x32_bf16 v[40:43], v[200:203], v[154:157], v[40:43]
	v_mfma_f32_16x16x32_bf16 v[32:35], v[218:221], v[154:157], v[32:35]
	v_mfma_f32_16x16x32_bf16 v[24:27], v[200:203], v[162:165], v[24:27]
	v_mfma_f32_16x16x32_bf16 v[20:23], v[218:221], v[162:165], v[20:23]
	v_mfma_f32_16x16x32_bf16 v[12:15], v[200:203], v[170:173], v[12:15]
	v_mfma_f32_16x16x32_bf16 v[8:11], v[218:221], v[170:173], v[8:11]
	v_mfma_f32_16x16x32_bf16 v[4:7], v[200:203], v[178:181], v[4:7]
	v_mfma_f32_16x16x32_bf16 v[0:3], v[218:221], v[178:181], v[0:3]
	v_mfma_f32_16x16x32_bf16 v[40:43], v[204:207], v[158:161], v[40:43]
	v_mfma_f32_16x16x32_bf16 v[32:35], v[222:225], v[158:161], v[32:35]
	v_mfma_f32_16x16x32_bf16 v[24:27], v[204:207], v[166:169], v[24:27]
	v_mfma_f32_16x16x32_bf16 v[20:23], v[222:225], v[166:169], v[20:23]
	v_mfma_f32_16x16x32_bf16 v[12:15], v[204:207], v[174:177], v[12:15]
	v_mfma_f32_16x16x32_bf16 v[8:11], v[222:225], v[174:177], v[8:11]
	v_mfma_f32_16x16x32_bf16 v[4:7], v[204:207], v[182:185], v[4:7]
	v_mfma_f32_16x16x32_bf16 v[0:3], v[222:225], v[182:185], v[0:3]
	s_add_i32 s27, s27, 2
	s_add_u32 s12, s12, 0x100
	s_addc_u32 s13, s13, 0
	s_add_u32 s1, s1, 0x100
	s_addc_u32 s5, s5, 0
	s_cmp_gt_u32 s27, 13
	s_barrier
	s_cbranch_scc0 .LBB0_1012
	s_cmpk_gt_u32 s2, 0xff
	s_cbranch_scc1 .Lal4_a
	s_barrier
